# hand-scheduled fast path for unmasked attention tiles (MLA and FoX): softmax VALU interleaved under QK/PV MFMA chains, decay subtract as plain v_sub
# speedup vs baseline: 1.0139x; 1.0139x over previous
; #define MFMA32(a, b, c) __builtin_amdgcn_mfma_f32_32x32x16_bf16((a), (b), (c), 0, 0, 0)
; #define ATT_ISSUE_K(j_) do { const int k0_ = (j_) * 64; \
;         _Pragma("unroll") for (int i = 0; i < NKL; ++i) { const int c = tid + i * NTHR, row = c / NKC, cc = c % NKC; pk_[i] = *(const u32x4*)(Kp + (size_t)(k0_ + row) * ldk + cc * 8); } \
;         if (DECAY && tid < 64) pc_ = cum[k0_ + tid] * LOG2E; } while (0)
;     ...
;         unsigned char* st = smem + (j & 1) * STAGE;
;         bf16_t* Ks = (bf16_t*)st; bf16_t* Vs = (bf16_t*)(st + 64 * KLD * 2); float* cks = (float*)(st + 64 * KLD * 2 + 128 * VLD * 2);
;         if (amode != 5 || j == 0) {
; #pragma unroll
;         for (int i = 0; i < NKL; ++i) { const int c = tid + i * NTHR, row = c / NKC, cc = c % NKC; *(u32x4*)(Ks + row * KLD + cc * 8) = pk_[i]; }
; #pragma unroll
;         for (int i = 0; i < 2; ++i) { const int c = tid + i * NTHR, row = c >> 3, cc = c & 7; u32x2 lo, hi; lo[0] = pv_[i][0]; lo[1] = pv_[i][1]; hi[0] = pv_[i][2]; hi[1] = pv_[i][3];
;             *(u32x2*)(Vs + row * VLD + cc * 8) = lo; *(u32x2*)(Vs + row * VLD + cc * 8 + 4) = hi; }
;         if (DECAY && tid < 64) cks[tid] = pc_;
;         }
;         __syncthreads();
;         const int k0 = j * 64;
;         const bool active = (k0 <= q0 + 31) && (amode != 4);
;         f32x16 sacc[2];
;         if (active) {
; #pragma unroll
;             for (int kb = 0; kb < 2; ++kb) {
;                 constexpr int NB = KS / 4;
;                 const bf16_t* kp = Ks + (32 * kb + r) * KLD + 8 * h2;
;                 bf16x8 kf[2][4];
; #pragma unroll
;                 for (int e = 0; e < 4; ++e) kf[0][e] = *(const bf16x8*)(kp + 16 * e);
;                 f32x16 acc; for (int i = 0; i < 16; ++i) acc[i] = 0.f;
; #pragma unroll
;                 for (int bb = 0; bb < NB; ++bb) {
;                     if (bb + 1 < NB) {
; #pragma unroll
;                         for (int e = 0; e < 4; ++e) kf[(bb + 1) & 1][e] = *(const bf16x8*)(kp + 16 * (4 * (bb + 1) + e)); }
;                     __builtin_amdgcn_sched_barrier(0);
; #pragma unroll
;                     for (int e = 0; e < 4; ++e) acc = MFMA32(kf[bb & 1][e], qf[4 * bb + e], acc);
;                     __builtin_amdgcn_sched_barrier(0);
;                 }
;                 sacc[kb] = acc;
;             }
;         }
;         if (j + 1 < ntiles && amode != 5) ATT_ISSUE_K(j + 1);
.LBB0_249:
	s_bitcmp1_b32 s60, 0
	s_cselect_b32 s0, 0x8900, 0
	s_add_i32 s41, s0, 0
	v_add3_u32 v0, s41, v207, v209
	s_waitcnt vmcnt(0)
	ds_write_b128 v0, v[214:217]
	v_add3_u32 v0, s41, v208, v210
	ds_write_b128 v0, v[222:225]
	v_lshl_add_u32 v0, v203, 1, s41
	s_movk_i32 s0, 0x4400
	v_add3_u32 v2, v0, v206, s0
	v_add3_u32 v0, v0, v205, s0
	ds_write2_b64 v2, v[244:245], v[246:247] offset1:1
	ds_write2_b64 v0, v[240:241], v[242:243] offset1:1
	s_and_saveexec_b64 s[0:1], vcc
	v_lshl_add_u32 v0, v196, 2, s41
	v_mul_f32_e32 v2, 0x3fb8aa3b, v201
	ds_write_b32 v0, v2 offset:34816
	s_or_b64 exec, exec, s[0:1]
	v_cmp_le_i32_e64 s[0:1], s40, v204
	s_add_i32 s98, s40, 63
	v_cmp_le_i32_e64 s[98:99], s98, v200
	s_waitcnt lgkmcnt(0)
	s_barrier
	v_add_u32_e32 v0, s40, v213
	v_mad_i64_i32 v[2:3], s[34:35], v0, s3, v[168:169]
	v_add_u32_e32 v0, s40, v212
	v_mad_i64_i32 v[4:5], s[34:35], v0, s3, v[170:171]
	global_load_dwordx4 v[214:217], v[2:3], off
	global_load_dwordx4 v[222:225], v[4:5], off
	s_add_i32 s4, s40, 64
	v_lshl_add_u64 v[2:3], s[4:5], 1, v[162:163]
	v_lshl_add_u64 v[4:5], v[2:3], 0, v[164:165]
	v_lshl_add_u64 v[2:3], v[2:3], 0, v[166:167]
	global_load_dwordx4 v[244:247], v[4:5], off
	global_load_dwordx4 v[240:243], v[2:3], off
	s_and_saveexec_b64 s[34:35], vcc
	s_cbranch_execz .Lfox_nocum
	v_add_u32_e32 v2, s40, v211
	v_ashrrev_i32_e32 v3, 31, v2
	v_lshl_add_u64 v[2:3], v[2:3], 2, s[24:25]
	global_load_dword v201, v[2:3], off
.Lfox_nocum:
	s_or_b64 exec, exec, s[34:35]
	s_and_b64 s[98:99], s[98:99], exec
	s_cbranch_scc1 .Lfox_fast
	s_and_saveexec_b64 s[34:35], s[0:1]
	s_cbranch_execz .LBB0_253
	v_add3_u32 v0, s41, v198, v202
	ds_read_b128 v[2:5], v0
	ds_read_b128 v[6:9], v0 offset:32
	ds_read_b128 v[10:13], v0 offset:64
	ds_read_b128 v[96:99], v0 offset:96
	ds_read_b128 v[100:103], v0 offset:128
	ds_read_b128 v[104:107], v0 offset:160
	ds_read_b128 v[108:111], v0 offset:192
	ds_read_b128 v[144:147], v0 offset:224
	s_waitcnt lgkmcnt(7)
	v_mfma_f32_32x32x16_bf16 v[80:95], v[2:5], v[140:143], 0
	s_waitcnt lgkmcnt(6)
	v_mfma_f32_32x32x16_bf16 v[80:95], v[6:9], v[136:139], v[80:95]
	s_waitcnt lgkmcnt(5)
	v_mfma_f32_32x32x16_bf16 v[80:95], v[10:13], v[132:135], v[80:95]
	s_waitcnt lgkmcnt(4)
	v_mfma_f32_32x32x16_bf16 v[80:95], v[96:99], v[128:131], v[80:95]
	s_waitcnt lgkmcnt(3)
	v_mfma_f32_32x32x16_bf16 v[80:95], v[100:103], v[124:127], v[80:95]
	s_waitcnt lgkmcnt(2)
	v_mfma_f32_32x32x16_bf16 v[80:95], v[104:107], v[120:123], v[80:95]
	s_waitcnt lgkmcnt(1)
	v_mfma_f32_32x32x16_bf16 v[80:95], v[108:111], v[116:119], v[80:95]
	s_waitcnt lgkmcnt(0)
	v_mfma_f32_32x32x16_bf16 v[80:95], v[144:147], v[112:115], v[80:95]
	ds_read_b128 v[2:5], v0 offset:8704
	ds_read_b128 v[6:9], v0 offset:8736
	ds_read_b128 v[10:13], v0 offset:8768
	ds_read_b128 v[144:147], v0 offset:8800
	ds_read_b128 v[148:151], v0 offset:8832
	ds_read_b128 v[152:155], v0 offset:8864
	ds_read_b128 v[156:159], v0 offset:8896
	ds_read_b128 v[172:175], v0 offset:8928
	s_waitcnt lgkmcnt(7)
	v_mfma_f32_32x32x16_bf16 v[96:111], v[2:5], v[140:143], 0
	s_waitcnt lgkmcnt(6)
	v_mfma_f32_32x32x16_bf16 v[96:111], v[6:9], v[136:139], v[96:111]
	s_waitcnt lgkmcnt(5)
	v_mfma_f32_32x32x16_bf16 v[96:111], v[10:13], v[132:135], v[96:111]
	s_waitcnt lgkmcnt(4)
	v_mfma_f32_32x32x16_bf16 v[96:111], v[144:147], v[128:131], v[96:111]
	s_waitcnt lgkmcnt(3)
	v_mfma_f32_32x32x16_bf16 v[96:111], v[148:151], v[124:127], v[96:111]
	s_waitcnt lgkmcnt(2)
	v_mfma_f32_32x32x16_bf16 v[96:111], v[152:155], v[120:123], v[96:111]
	s_waitcnt lgkmcnt(1)
	v_mfma_f32_32x32x16_bf16 v[96:111], v[156:159], v[116:119], v[96:111]
	s_waitcnt lgkmcnt(0)
	v_mfma_f32_32x32x16_bf16 v[96:111], v[172:175], v[112:115], v[96:111]

;     ...
;         if (active) {
; #pragma unroll
;             for (int kb = 0; kb < 2; ++kb) {
;                 constexpr int NB = KS / 4;
;                 const bf16_t* kp = Ks + (32 * kb + r) * KLD + 8 * h2;
;                 bf16x8 kf[2][4];
; #pragma unroll
;                 for (int e = 0; e < 4; ++e) kf[0][e] = *(const bf16x8*)(kp + 16 * e);
;                 f32x16 acc; for (int i = 0; i < 16; ++i) acc[i] = 0.f;
; #pragma unroll
;                 for (int bb = 0; bb < NB; ++bb) {
;                     if (bb + 1 < NB) {
; #pragma unroll
;                         for (int e = 0; e < 4; ++e) kf[(bb + 1) & 1][e] = *(const bf16x8*)(kp + 16 * (4 * (bb + 1) + e)); }
;                     __builtin_amdgcn_sched_barrier(0);
; #pragma unroll
;                     for (int e = 0; e < 4; ++e) acc = MFMA32(kf[bb & 1][e], qf[4 * bb + e], acc);
;                     __builtin_amdgcn_sched_barrier(0);
;                 }
;                 sacc[kb] = acc;
;             }
;         }
;         if (j + 1 < ntiles && amode != 5) ATT_ISSUE_K(j + 1);
;         if (active) {
;             const bool masked = (k0 + 63 > q0); const int qpos = q0 + r;
; #pragma unroll
;             for (int kb = 0; kb < 2; ++kb) {
;                 bf16x8 vfa[2][2], vfb[2][2];
; #pragma unroll
;                 for (int d = 0; d < 2; ++d) { vfa[d][0] = ld_perm(Vs + (32 * d + r) * VLD + 32 * kb + 4 * h2); vfa[d][1] = ld_perm(Vs + (32 * d + r) * VLD + 32 * kb + 16 + 4 * h2); }
;                 f32x4 c4[2];
;                 if (DECAY) {
; #pragma unroll
;                     for (int g = 0; g < 2; ++g) c4[g] = *(const f32x4*)(cks + 32 * kb + 8 * g + 4 * h2); }
;                 __builtin_amdgcn_sched_barrier(0);
;                 if (DECAY) {
; #pragma unroll
;                     for (int g = 0; g < 2; ++g)
; #pragma unroll
;                         for (int e = 0; e < 4; ++e) sacc[kb][4 * g + e] -= c4[g][e];
; #pragma unroll
;                     for (int g = 0; g < 2; ++g) c4[g] = *(const f32x4*)(cks + 32 * kb + 8 * (g + 2) + 4 * h2);
; #pragma unroll
;                     for (int g = 0; g < 2; ++g)
; #pragma unroll
;                         for (int e = 0; e < 4; ++e) sacc[kb][4 * (g + 2) + e] -= c4[g][e];
;                 }
;                 if (masked) {
; #pragma unroll
;                     for (int i = 0; i < 16; ++i) { if (k0 + 32 * kb + crow(i, h2) > qpos) sacc[kb][i] = -INFINITY; } }
.Lfox_fast:
	v_add3_u32 v0, s41, v198, v202
	ds_read_b128 v[2:5], v0
	ds_read_b128 v[6:9], v0 offset:32
	ds_read_b128 v[10:13], v0 offset:64
	ds_read_b128 v[96:99], v0 offset:96
	ds_read_b128 v[100:103], v0 offset:128
	ds_read_b128 v[104:107], v0 offset:160
	ds_read_b128 v[108:111], v0 offset:192
	ds_read_b128 v[144:147], v0 offset:224
	s_waitcnt lgkmcnt(7)
	v_mfma_f32_32x32x16_bf16 v[80:95], v[2:5], v[140:143], 0
	s_waitcnt lgkmcnt(6)
	v_mfma_f32_32x32x16_bf16 v[80:95], v[6:9], v[136:139], v[80:95]
	s_waitcnt lgkmcnt(5)
	v_mfma_f32_32x32x16_bf16 v[80:95], v[10:13], v[132:135], v[80:95]
	s_waitcnt lgkmcnt(4)
	v_mfma_f32_32x32x16_bf16 v[80:95], v[96:99], v[128:131], v[80:95]
	s_waitcnt lgkmcnt(3)
	v_mfma_f32_32x32x16_bf16 v[80:95], v[100:103], v[124:127], v[80:95]
	s_waitcnt lgkmcnt(2)
	v_mfma_f32_32x32x16_bf16 v[80:95], v[104:107], v[120:123], v[80:95]
	s_waitcnt lgkmcnt(1)
	v_mfma_f32_32x32x16_bf16 v[80:95], v[108:111], v[116:119], v[80:95]
	s_waitcnt lgkmcnt(0)
	v_mfma_f32_32x32x16_bf16 v[80:95], v[144:147], v[112:115], v[80:95]
	ds_read_b128 v[2:5], v0 offset:8704
	ds_read_b128 v[6:9], v0 offset:8736
	ds_read_b128 v[10:13], v0 offset:8768
	ds_read_b128 v[144:147], v0 offset:8800
	ds_read_b128 v[148:151], v0 offset:8832
	ds_read_b128 v[152:155], v0 offset:8864
	ds_read_b128 v[156:159], v0 offset:8896
	ds_read_b128 v[172:175], v0 offset:8928
	v_add_u32_e32 v232, s41, v198
	ds_read_b128 v[176:179], v232 offset:34816
	ds_read_b128 v[186:189], v232 offset:34848
	ds_read_b128 v[236:239], v232 offset:34880
	ds_read_b128 v[232:235], v232 offset:34912
	s_waitcnt lgkmcnt(11)
	v_mfma_f32_32x32x16_bf16 v[96:111], v[2:5], v[140:143], 0
	s_waitcnt lgkmcnt(10)
	v_mfma_f32_32x32x16_bf16 v[96:111], v[6:9], v[136:139], v[96:111]
	s_waitcnt lgkmcnt(0)
	v_sub_f32_e32 v192, v80, v176
	v_add_f32_e32 v192, v182, v192
	v_exp_f32_e32 v80, v192
	v_mfma_f32_32x32x16_bf16 v[96:111], v[10:13], v[132:135], v[96:111]
	v_sub_f32_e32 v193, v81, v177
	v_add_f32_e32 v193, v182, v193
	v_exp_f32_e32 v81, v193
	v_sub_f32_e32 v192, v82, v178
	v_add_f32_e32 v192, v182, v192
	v_exp_f32_e32 v82, v192
	v_sub_f32_e32 v193, v83, v179
	v_add_f32_e32 v193, v182, v193
	v_exp_f32_e32 v83, v193
	v_mfma_f32_32x32x16_bf16 v[96:111], v[144:147], v[128:131], v[96:111]
	v_sub_f32_e32 v192, v84, v186
	v_add_f32_e32 v192, v182, v192
	v_exp_f32_e32 v84, v192
	v_sub_f32_e32 v193, v85, v187
	v_add_f32_e32 v193, v182, v193
	v_exp_f32_e32 v85, v193
	v_sub_f32_e32 v192, v86, v188
	v_add_f32_e32 v192, v182, v192
	v_exp_f32_e32 v86, v192
	v_mfma_f32_32x32x16_bf16 v[96:111], v[148:151], v[124:127], v[96:111]
	v_sub_f32_e32 v193, v87, v189
	v_add_f32_e32 v193, v182, v193
	v_exp_f32_e32 v87, v193
	v_sub_f32_e32 v192, v88, v236
	v_add_f32_e32 v192, v182, v192
	v_exp_f32_e32 v88, v192
	v_sub_f32_e32 v193, v89, v237
	v_add_f32_e32 v193, v182, v193
	v_exp_f32_e32 v89, v193
	v_mfma_f32_32x32x16_bf16 v[96:111], v[152:155], v[120:123], v[96:111]
	v_sub_f32_e32 v192, v90, v238
	v_add_f32_e32 v192, v182, v192
	v_exp_f32_e32 v90, v192
	v_sub_f32_e32 v193, v91, v239
	v_add_f32_e32 v193, v182, v193
	v_exp_f32_e32 v91, v193
	v_sub_f32_e32 v192, v92, v232
	v_add_f32_e32 v192, v182, v192
	v_exp_f32_e32 v92, v192
	v_mfma_f32_32x32x16_bf16 v[96:111], v[156:159], v[116:119], v[96:111]
	v_sub_f32_e32 v193, v93, v233
	v_add_f32_e32 v193, v182, v193
	v_exp_f32_e32 v93, v193
	v_sub_f32_e32 v192, v94, v234
	v_add_f32_e32 v192, v182, v192
	v_exp_f32_e32 v94, v192
	v_sub_f32_e32 v193, v95, v235
	v_add_f32_e32 v193, v182, v193
	v_exp_f32_e32 v95, v193
	v_mfma_f32_32x32x16_bf16 v[96:111], v[172:175], v[112:115], v[96:111]
	v_cvt_pk_bf16_f32 v148, v80, v81
	v_cvt_pk_bf16_f32 v149, v82, v83
	v_cvt_pk_bf16_f32 v150, v84, v85
	v_cvt_pk_bf16_f32 v151, v86, v87
	v_cvt_pk_bf16_f32 v152, v88, v89
	v_cvt_pk_bf16_f32 v153, v90, v91
	v_cvt_pk_bf16_f32 v154, v92, v93
	v_cvt_pk_bf16_f32 v155, v94, v95
	v_add_u32_e32 v232, s41, v198
	ds_read_b128 v[156:159], v232 offset:34944
	ds_read_b128 v[172:175], v232 offset:34976
	ds_read_b128 v[176:179], v232 offset:35008
	ds_read_b128 v[186:189], v232 offset:35040
	v_lshlrev_b32_e32 v0, 1, v197
	v_add3_u32 v14, s41, v199, v0
	v_add_u32_e32 v15, 0x4000, v14
	v_add_u32_e32 v0, 0x5000, v14
	ds_read2_b64 v[2:5], v15 offset0:128 offset1:130
	ds_read2_b64 v[6:9], v15 offset0:132 offset1:134
	ds_read2_b64 v[10:13], v0 offset0:160 offset1:162
	ds_read2_b64 v[144:147], v0 offset0:164 offset1:166
	v_add_u32_e32 v236, 0x6000, v14
	v_add_u32_e32 v237, 0x7000, v14
	s_waitcnt lgkmcnt(3)
;     ...
;         if (active) {
;             const bool masked = (k0 + 63 > q0); const int qpos = q0 + r;
; #pragma unroll
;             for (int kb = 0; kb < 2; ++kb) {
;                 bf16x8 vfa[2][2], vfb[2][2];
; #pragma unroll
;                 for (int d = 0; d < 2; ++d) { vfa[d][0] = ld_perm(Vs + (32 * d + r) * VLD + 32 * kb + 4 * h2); vfa[d][1] = ld_perm(Vs + (32 * d + r) * VLD + 32 * kb + 16 + 4 * h2); }
;                 f32x4 c4[2];
;                 if (DECAY) {
; #pragma unroll
;                     for (int g = 0; g < 2; ++g) c4[g] = *(const f32x4*)(cks + 32 * kb + 8 * g + 4 * h2); }
;                 __builtin_amdgcn_sched_barrier(0);
;                 if (DECAY) {
; #pragma unroll
;                     for (int g = 0; g < 2; ++g)
; #pragma unroll
;                         for (int e = 0; e < 4; ++e) sacc[kb][4 * g + e] -= c4[g][e];
; #pragma unroll
;                     for (int g = 0; g < 2; ++g) c4[g] = *(const f32x4*)(cks + 32 * kb + 8 * (g + 2) + 4 * h2);
; #pragma unroll
;                     for (int g = 0; g < 2; ++g)
; #pragma unroll
;                         for (int e = 0; e < 4; ++e) sacc[kb][4 * (g + 2) + e] -= c4[g][e];
;                 }
;                 if (masked) {
; #pragma unroll
;                     for (int i = 0; i < 16; ++i) { if (k0 + 32 * kb + crow(i, h2) > qpos) sacc[kb][i] = -INFINITY; } }
;                 float rs = 0.f;
; #pragma unroll
;                 for (int i = 0; i < 16; ++i) { const float pz = __builtin_amdgcn_exp2f(sacc[kb][i] + c0); sacc[kb][i] = pz; rs += pz; }
;                 l_run += rs;
;                 const bf16x8 pf0 = pack8(sacc[kb], 0), pf1 = pack8(sacc[kb], 1);
;                 __builtin_amdgcn_sched_barrier(0);
; #pragma unroll
;                 for (int d = 0; d < 2; ++d) { oacc[d] = MFMA32(vfa[d][0], pf0, oacc[d]); oacc[d] = MFMA32(vfa[d][1], pf1, oacc[d]); }
; #pragma unroll
;                 for (int d = 0; d < 2; ++d) { vfb[d][0] = ld_perm(Vs + (32 * (d + 2) + r) * VLD + 32 * kb + 4 * h2); vfb[d][1] = ld_perm(Vs + (32 * (d + 2) + r) * VLD + 32 * kb + 16 + 4 * h2); }
;                 if (kb == 1 && j + 1 < ntiles && amode != 5) ATT_ISSUE_V(j + 1);
;                 __builtin_amdgcn_sched_barrier(0);
; #pragma unroll
;                 for (int d = 0; d < 2; ++d) { oacc[d + 2] = MFMA32(vfb[d][0], pf0, oacc[d + 2]); oacc[d + 2] = MFMA32(vfb[d][1], pf1, oacc[d + 2]); }
;             }
	v_mfma_f32_32x32x16_bf16 v[64:79], v[2:5], v[148:151], v[64:79]
	v_sub_f32_e32 v192, v96, v156
	v_add_f32_e32 v192, v182, v192
	v_exp_f32_e32 v96, v192
	v_sub_f32_e32 v193, v97, v157
	v_add_f32_e32 v193, v182, v193
	v_exp_f32_e32 v97, v193
	s_waitcnt lgkmcnt(1)
	v_mfma_f32_32x32x16_bf16 v[48:63], v[10:13], v[148:151], v[48:63]
	v_sub_f32_e32 v192, v98, v158
	v_add_f32_e32 v192, v182, v192
	v_exp_f32_e32 v98, v192
	v_sub_f32_e32 v193, v99, v159
	v_add_f32_e32 v193, v182, v193
	v_exp_f32_e32 v99, v193
	v_mfma_f32_32x32x16_bf16 v[64:79], v[6:9], v[152:155], v[64:79]
	ds_read2_b64 v[2:5], v237 offset0:228 offset1:230
	ds_read2_b64 v[6:9], v237 offset0:224 offset1:226
	v_sub_f32_e32 v192, v100, v172
	v_add_f32_e32 v192, v182, v192
	v_exp_f32_e32 v100, v192
	v_sub_f32_e32 v193, v101, v173
	v_add_f32_e32 v193, v182, v193
	v_exp_f32_e32 v101, v193
	s_waitcnt lgkmcnt(2)
	v_mfma_f32_32x32x16_bf16 v[48:63], v[144:147], v[152:155], v[48:63]
	ds_read2_b64 v[10:13], v236 offset0:192 offset1:194
	ds_read2_b64 v[144:147], v236 offset0:196 offset1:198
	v_sub_f32_e32 v192, v102, v174
	v_add_f32_e32 v192, v182, v192
	v_exp_f32_e32 v102, v192
	v_sub_f32_e32 v193, v103, v175
	v_add_f32_e32 v193, v182, v193
	v_exp_f32_e32 v103, v193
	s_waitcnt lgkmcnt(1)
	v_mfma_f32_32x32x16_bf16 v[32:47], v[10:13], v[148:151], v[32:47]
	v_sub_f32_e32 v192, v104, v176
	v_add_f32_e32 v192, v182, v192
	v_exp_f32_e32 v104, v192
	v_sub_f32_e32 v193, v105, v177
	v_add_f32_e32 v193, v182, v193
	v_exp_f32_e32 v105, v193
	v_mfma_f32_32x32x16_bf16 v[16:31], v[6:9], v[148:151], v[16:31]
	v_sub_f32_e32 v192, v106, v178
	v_add_f32_e32 v192, v182, v192
	v_exp_f32_e32 v106, v192
	v_sub_f32_e32 v193, v107, v179
	v_add_f32_e32 v193, v182, v193
	v_exp_f32_e32 v107, v193
	s_waitcnt lgkmcnt(0)
	v_mfma_f32_32x32x16_bf16 v[32:47], v[144:147], v[152:155], v[32:47]
	ds_read2_b64 v[6:9], v15 offset0:136 offset1:138
	ds_read2_b64 v[10:13], v15 offset0:140 offset1:142
	ds_read2_b64 v[144:147], v0 offset0:168 offset1:170
	ds_read2_b64 v[232:235], v0 offset0:172 offset1:174
	v_sub_f32_e32 v192, v108, v186
	v_add_f32_e32 v192, v182, v192
	v_exp_f32_e32 v108, v192
	v_sub_f32_e32 v193, v109, v187
	v_add_f32_e32 v193, v182, v193
	v_exp_f32_e32 v109, v193
	v_mfma_f32_32x32x16_bf16 v[16:31], v[2:5], v[152:155], v[16:31]
	v_sub_f32_e32 v192, v110, v188
	v_add_f32_e32 v192, v182, v192
	v_exp_f32_e32 v110, v192
	v_sub_f32_e32 v193, v111, v189
	v_add_f32_e32 v193, v182, v193
	v_exp_f32_e32 v111, v193
	v_cvt_pk_bf16_f32 v2, v96, v97
	v_cvt_pk_bf16_f32 v3, v98, v99
	v_cvt_pk_bf16_f32 v4, v100, v101
	v_cvt_pk_bf16_f32 v5, v102, v103
	v_cvt_pk_bf16_f32 v148, v104, v105
	v_cvt_pk_bf16_f32 v149, v106, v107
	v_cvt_pk_bf16_f32 v150, v108, v109
	v_cvt_pk_bf16_f32 v151, v110, v111
	s_waitcnt lgkmcnt(3)
	v_mfma_f32_32x32x16_bf16 v[64:79], v[6:9], v[2:5], v[64:79]
	v_add_f32_e32 v192, 0, v80
	v_add_f32_e32 v193, 0, v96
	v_add_f32_e32 v192, v81, v192
	v_add_f32_e32 v193, v97, v193
	s_waitcnt lgkmcnt(1)
	v_mfma_f32_32x32x16_bf16 v[48:63], v[144:147], v[2:5], v[48:63]
	v_add_f32_e32 v192, v82, v192
	v_add_f32_e32 v193, v98, v193
	v_add_f32_e32 v192, v83, v192
	v_add_f32_e32 v193, v99, v193
	v_mfma_f32_32x32x16_bf16 v[64:79], v[10:13], v[148:151], v[64:79]
	ds_read2_b64 v[6:9], v236 offset0:200 offset1:202
	ds_read2_b64 v[10:13], v236 offset0:204 offset1:206
	ds_read2_b64 v[144:147], v237 offset0:232 offset1:234
	ds_read2_b64 v[152:155], v237 offset0:236 offset1:238
	v_add_f32_e32 v192, v84, v192
	v_add_f32_e32 v193, v100, v193
	v_add_f32_e32 v192, v85, v192
	v_add_f32_e32 v193, v101, v193
	s_waitcnt lgkmcnt(4)
	v_mfma_f32_32x32x16_bf16 v[48:63], v[232:235], v[148:151], v[48:63]
	v_add_f32_e32 v192, v86, v192
	v_add_f32_e32 v193, v102, v193
	v_add_f32_e32 v192, v87, v192
	v_add_f32_e32 v193, v103, v193
	s_waitcnt lgkmcnt(3)
	v_mfma_f32_32x32x16_bf16 v[32:47], v[6:9], v[2:5], v[32:47]
	v_add_f32_e32 v192, v88, v192
	v_add_f32_e32 v193, v104, v193
	v_add_f32_e32 v192, v89, v192
	v_add_f32_e32 v193, v105, v193
	s_waitcnt lgkmcnt(1)
	v_mfma_f32_32x32x16_bf16 v[16:31], v[144:147], v[2:5], v[16:31]
	v_add_f32_e32 v192, v90, v192
	v_add_f32_e32 v193, v106, v193
	v_add_f32_e32 v192, v91, v192
	v_add_f32_e32 v193, v107, v193
	v_mfma_f32_32x32x16_bf16 v[32:47], v[10:13], v[148:151], v[32:47]
	v_add_f32_e32 v192, v92, v192
	v_add_f32_e32 v193, v108, v193
	v_add_f32_e32 v192, v93, v192
	v_add_f32_e32 v193, v109, v193
	s_waitcnt lgkmcnt(0)
	v_mfma_f32_32x32x16_bf16 v[16:31], v[152:155], v[148:151], v[16:31]
	v_add_f32_e32 v192, v94, v192
	v_add_f32_e32 v193, v110, v193
	v_add_f32_e32 v192, v95, v192
	v_add_f32_e32 v193, v111, v193
	v_add_f32_e32 v192, v183, v192
	v_add_f32_e32 v183, v192, v193
	s_branch .LBB0_257

; #define MFMA32(a, b, c) __builtin_amdgcn_mfma_f32_32x32x16_bf16((a), (b), (c), 0, 0, 0)
;     ...
;         unsigned char* st = smem + (j & 1) * STAGE;
;         bf16_t* Ks = (bf16_t*)st; bf16_t* Vs = (bf16_t*)(st + 64 * KLD * 2); float* cks = (float*)(st + 64 * KLD * 2 + 128 * VLD * 2);
;         if (amode != 5 || j == 0) {
; #pragma unroll
;         for (int i = 0; i < NKL; ++i) { const int c = tid + i * NTHR, row = c / NKC, cc = c % NKC; *(u32x4*)(Ks + row * KLD + cc * 8) = pk_[i]; }
; #pragma unroll
;         for (int i = 0; i < 2; ++i) { const int c = tid + i * NTHR, row = c >> 3, cc = c & 7; u32x2 lo, hi; lo[0] = pv_[i][0]; lo[1] = pv_[i][1]; hi[0] = pv_[i][2]; hi[1] = pv_[i][3];
;             *(u32x2*)(Vs + row * VLD + cc * 8) = lo; *(u32x2*)(Vs + row * VLD + cc * 8 + 4) = hi; }
;         if (DECAY && tid < 64) cks[tid] = pc_;
;         }
;         __syncthreads();
;         const int k0 = j * 64;
;         const bool active = (k0 <= q0 + 31) && (amode != 4);
;         f32x16 sacc[2];
;         if (active) {
; #pragma unroll
;             for (int kb = 0; kb < 2; ++kb) {
;                 constexpr int NB = KS / 4;
;                 const bf16_t* kp = Ks + (32 * kb + r) * KLD + 8 * h2;
;                 bf16x8 kf[2][4];
; #pragma unroll
;                 for (int e = 0; e < 4; ++e) kf[0][e] = *(const bf16x8*)(kp + 16 * e);
;                 f32x16 acc; for (int i = 0; i < 16; ++i) acc[i] = 0.f;
; #pragma unroll
;                 for (int bb = 0; bb < NB; ++bb) {
;                     if (bb + 1 < NB) {
; #pragma unroll
;                         for (int e = 0; e < 4; ++e) kf[(bb + 1) & 1][e] = *(const bf16x8*)(kp + 16 * (4 * (bb + 1) + e)); }
;                     __builtin_amdgcn_sched_barrier(0);
; #pragma unroll
;                     for (int e = 0; e < 4; ++e) acc = MFMA32(kf[bb & 1][e], qf[4 * bb + e], acc);
;                     __builtin_amdgcn_sched_barrier(0);
;                 }
;                 sacc[kb] = acc;
;             }
;         }
.LBB0_291:
	s_bitcmp1_b32 s41, 0
	s_cselect_b32 s0, 0xa900, 0
	s_add_i32 s35, s0, 0
	v_add3_u32 v0, s35, v239, v242
	s_waitcnt vmcnt(2)
	ds_write_b128 v0, v[164:167]
	v_add3_u32 v0, s35, v240, v243
	s_waitcnt vmcnt(1)
	ds_write_b128 v0, v[160:163]
	v_add3_u32 v0, s35, v244, v245
	s_waitcnt vmcnt(0)
	ds_write_b128 v0, v[168:171]
	v_lshl_add_u32 v0, v235, 1, s35
	s_movk_i32 s0, 0x6400
	v_add3_u32 v2, v0, v241, s0
	v_add3_u32 v0, v0, v238, s0
	v_cmp_le_i32_e32 vcc, s34, v236
	s_add_i32 s98, s34, 63
	v_cmp_le_i32_e64 s[98:99], s98, v232
	s_waitcnt vmcnt(1)
	ds_write2_b64 v2, v[176:177], v[178:179] offset1:1
	s_waitcnt vmcnt(0)
	ds_write2_b64 v0, v[172:173], v[174:175] offset1:1
	s_waitcnt lgkmcnt(0)
	s_barrier
	s_and_b64 s[98:99], s[98:99], exec
	s_cbranch_scc1 .Lmla_fast
	s_and_saveexec_b64 s[0:1], vcc
	s_cbranch_execz .LBB0_293
	v_add3_u32 v0, s35, v198, v237
	ds_read_b128 v[2:5], v0
	ds_read_b128 v[6:9], v0 offset:32
	ds_read_b128 v[10:13], v0 offset:64
	ds_read_b128 v[96:99], v0 offset:96
	ds_read_b128 v[100:103], v0 offset:128
	ds_read_b128 v[104:107], v0 offset:160
	ds_read_b128 v[108:111], v0 offset:192
	ds_read_b128 v[160:163], v0 offset:224
	s_waitcnt lgkmcnt(7)
	v_mfma_f32_32x32x16_bf16 v[80:95], v[2:5], v[156:159], 0
	s_waitcnt lgkmcnt(6)
	v_mfma_f32_32x32x16_bf16 v[80:95], v[6:9], v[152:155], v[80:95]
	s_waitcnt lgkmcnt(5)
	v_mfma_f32_32x32x16_bf16 v[80:95], v[10:13], v[148:151], v[80:95]
	s_waitcnt lgkmcnt(4)
	v_mfma_f32_32x32x16_bf16 v[80:95], v[96:99], v[144:147], v[80:95]
	ds_read_b128 v[2:5], v0 offset:256
	ds_read_b128 v[6:9], v0 offset:288
	ds_read_b128 v[10:13], v0 offset:320
	ds_read_b128 v[96:99], v0 offset:352
	s_waitcnt lgkmcnt(7)
	v_mfma_f32_32x32x16_bf16 v[80:95], v[100:103], v[140:143], v[80:95]
	s_waitcnt lgkmcnt(6)
	v_mfma_f32_32x32x16_bf16 v[80:95], v[104:107], v[136:139], v[80:95]
	s_waitcnt lgkmcnt(5)
	v_mfma_f32_32x32x16_bf16 v[80:95], v[108:111], v[132:135], v[80:95]
	s_waitcnt lgkmcnt(4)
	v_mfma_f32_32x32x16_bf16 v[80:95], v[160:163], v[128:131], v[80:95]
	s_waitcnt lgkmcnt(3)
	v_mfma_f32_32x32x16_bf16 v[80:95], v[2:5], v[124:127], v[80:95]
	s_waitcnt lgkmcnt(2)
	v_mfma_f32_32x32x16_bf16 v[80:95], v[6:9], v[120:123], v[80:95]
	s_waitcnt lgkmcnt(1)
	v_mfma_f32_32x32x16_bf16 v[80:95], v[10:13], v[116:119], v[80:95]
	s_waitcnt lgkmcnt(0)
	v_mfma_f32_32x32x16_bf16 v[80:95], v[96:99], v[112:115], v[80:95]
	ds_read_b128 v[2:5], v0 offset:12800
	ds_read_b128 v[6:9], v0 offset:12832
	ds_read_b128 v[10:13], v0 offset:12864
	ds_read_b128 v[160:163], v0 offset:12896
	ds_read_b128 v[164:167], v0 offset:12928
	ds_read_b128 v[168:171], v0 offset:12960
	ds_read_b128 v[172:175], v0 offset:12992
	ds_read_b128 v[176:179], v0 offset:13024
	s_waitcnt lgkmcnt(7)
	v_mfma_f32_32x32x16_bf16 v[96:111], v[2:5], v[156:159], 0
	s_waitcnt lgkmcnt(6)
	v_mfma_f32_32x32x16_bf16 v[96:111], v[6:9], v[152:155], v[96:111]
	s_waitcnt lgkmcnt(5)
	v_mfma_f32_32x32x16_bf16 v[96:111], v[10:13], v[148:151], v[96:111]
	s_waitcnt lgkmcnt(4)
	v_mfma_f32_32x32x16_bf16 v[96:111], v[160:163], v[144:147], v[96:111]
	ds_read_b128 v[2:5], v0 offset:13056
	ds_read_b128 v[6:9], v0 offset:13088
	ds_read_b128 v[10:13], v0 offset:13120
	ds_read_b128 v[160:163], v0 offset:13152
	s_waitcnt lgkmcnt(7)
	v_mfma_f32_32x32x16_bf16 v[96:111], v[164:167], v[140:143], v[96:111]
	s_waitcnt lgkmcnt(6)
	v_mfma_f32_32x32x16_bf16 v[96:111], v[168:171], v[136:139], v[96:111]
	s_waitcnt lgkmcnt(5)
	v_mfma_f32_32x32x16_bf16 v[96:111], v[172:175], v[132:135], v[96:111]
	s_waitcnt lgkmcnt(4)
	v_mfma_f32_32x32x16_bf16 v[96:111], v[176:179], v[128:131], v[96:111]
	s_waitcnt lgkmcnt(3)
	v_mfma_f32_32x32x16_bf16 v[96:111], v[2:5], v[124:127], v[96:111]
	s_waitcnt lgkmcnt(2)
	v_mfma_f32_32x32x16_bf16 v[96:111], v[6:9], v[120:123], v[96:111]
	s_waitcnt lgkmcnt(1)
	v_mfma_f32_32x32x16_bf16 v[96:111], v[10:13], v[116:119], v[96:111]
	s_waitcnt lgkmcnt(0)
	v_mfma_f32_32x32x16_bf16 v[96:111], v[160:163], v[112:115], v[96:111]

;     ...
;         if (active) {
; #pragma unroll
;             for (int kb = 0; kb < 2; ++kb) {
;                 constexpr int NB = KS / 4;
;                 const bf16_t* kp = Ks + (32 * kb + r) * KLD + 8 * h2;
;                 bf16x8 kf[2][4];
; #pragma unroll
;                 for (int e = 0; e < 4; ++e) kf[0][e] = *(const bf16x8*)(kp + 16 * e);
;                 f32x16 acc; for (int i = 0; i < 16; ++i) acc[i] = 0.f;
; #pragma unroll
;                 for (int bb = 0; bb < NB; ++bb) {
;                     if (bb + 1 < NB) {
; #pragma unroll
;                         for (int e = 0; e < 4; ++e) kf[(bb + 1) & 1][e] = *(const bf16x8*)(kp + 16 * (4 * (bb + 1) + e)); }
;                     __builtin_amdgcn_sched_barrier(0);
; #pragma unroll
;                     for (int e = 0; e < 4; ++e) acc = MFMA32(kf[bb & 1][e], qf[4 * bb + e], acc);
;                     __builtin_amdgcn_sched_barrier(0);
;                 }
;                 sacc[kb] = acc;
;             }
;         }
;         if (j + 1 < ntiles && amode != 5) ATT_ISSUE_K(j + 1);
;         if (active) {
;             const bool masked = (k0 + 63 > q0); const int qpos = q0 + r;
; #pragma unroll
;             for (int kb = 0; kb < 2; ++kb) {
;                 bf16x8 vfa[2][2], vfb[2][2];
; #pragma unroll
;                 for (int d = 0; d < 2; ++d) { vfa[d][0] = ld_perm(Vs + (32 * d + r) * VLD + 32 * kb + 4 * h2); vfa[d][1] = ld_perm(Vs + (32 * d + r) * VLD + 32 * kb + 16 + 4 * h2); }
;                 f32x4 c4[2];
;                 if (DECAY) {
; #pragma unroll
;                     for (int g = 0; g < 2; ++g) c4[g] = *(const f32x4*)(cks + 32 * kb + 8 * g + 4 * h2); }
;                 __builtin_amdgcn_sched_barrier(0);
;                 if (DECAY) {
; #pragma unroll
;                     for (int g = 0; g < 2; ++g)
; #pragma unroll
;                         for (int e = 0; e < 4; ++e) sacc[kb][4 * g + e] -= c4[g][e];
; #pragma unroll
;                     for (int g = 0; g < 2; ++g) c4[g] = *(const f32x4*)(cks + 32 * kb + 8 * (g + 2) + 4 * h2);
; #pragma unroll
;                     for (int g = 0; g < 2; ++g)
; #pragma unroll
;                         for (int e = 0; e < 4; ++e) sacc[kb][4 * (g + 2) + e] -= c4[g][e];
;                 }
;                 if (masked) {
; #pragma unroll
;                     for (int i = 0; i < 16; ++i) { if (k0 + 32 * kb + crow(i, h2) > qpos) sacc[kb][i] = -INFINITY; } }
.Lmla_fast:
	v_add3_u32 v0, s35, v198, v237
	ds_read_b128 v[2:5], v0
	ds_read_b128 v[6:9], v0 offset:32
	ds_read_b128 v[10:13], v0 offset:64
	ds_read_b128 v[96:99], v0 offset:96
	ds_read_b128 v[100:103], v0 offset:128
	ds_read_b128 v[104:107], v0 offset:160
	ds_read_b128 v[108:111], v0 offset:192
	ds_read_b128 v[160:163], v0 offset:224
	s_waitcnt lgkmcnt(7)
	v_mfma_f32_32x32x16_bf16 v[80:95], v[2:5], v[156:159], 0
	s_waitcnt lgkmcnt(6)
	v_mfma_f32_32x32x16_bf16 v[80:95], v[6:9], v[152:155], v[80:95]
	s_waitcnt lgkmcnt(5)
	v_mfma_f32_32x32x16_bf16 v[80:95], v[10:13], v[148:151], v[80:95]
	s_waitcnt lgkmcnt(4)
	v_mfma_f32_32x32x16_bf16 v[80:95], v[96:99], v[144:147], v[80:95]
	ds_read_b128 v[2:5], v0 offset:256
	ds_read_b128 v[6:9], v0 offset:288
	ds_read_b128 v[10:13], v0 offset:320
	ds_read_b128 v[96:99], v0 offset:352
	s_waitcnt lgkmcnt(7)
	v_mfma_f32_32x32x16_bf16 v[80:95], v[100:103], v[140:143], v[80:95]
	s_waitcnt lgkmcnt(6)
	v_mfma_f32_32x32x16_bf16 v[80:95], v[104:107], v[136:139], v[80:95]
	s_waitcnt lgkmcnt(5)
	v_mfma_f32_32x32x16_bf16 v[80:95], v[108:111], v[132:135], v[80:95]
	s_waitcnt lgkmcnt(4)
	v_mfma_f32_32x32x16_bf16 v[80:95], v[160:163], v[128:131], v[80:95]
	s_waitcnt lgkmcnt(3)
	v_mfma_f32_32x32x16_bf16 v[80:95], v[2:5], v[124:127], v[80:95]
	s_waitcnt lgkmcnt(2)
	v_mfma_f32_32x32x16_bf16 v[80:95], v[6:9], v[120:123], v[80:95]
	s_waitcnt lgkmcnt(1)
	v_mfma_f32_32x32x16_bf16 v[80:95], v[10:13], v[116:119], v[80:95]
	s_waitcnt lgkmcnt(0)
	v_mfma_f32_32x32x16_bf16 v[80:95], v[96:99], v[112:115], v[80:95]
	ds_read_b128 v[2:5], v0 offset:12800
	ds_read_b128 v[6:9], v0 offset:12832
	ds_read_b128 v[10:13], v0 offset:12864
	ds_read_b128 v[160:163], v0 offset:12896
	ds_read_b128 v[164:167], v0 offset:12928
	ds_read_b128 v[168:171], v0 offset:12960
	ds_read_b128 v[172:175], v0 offset:12992
	ds_read_b128 v[176:179], v0 offset:13024
	s_waitcnt lgkmcnt(7)
	v_mfma_f32_32x32x16_bf16 v[96:111], v[2:5], v[156:159], 0
	s_waitcnt lgkmcnt(6)
	v_mfma_f32_32x32x16_bf16 v[96:111], v[6:9], v[152:155], v[96:111]
	s_waitcnt lgkmcnt(5)
	v_mfma_f32_32x32x16_bf16 v[96:111], v[10:13], v[148:151], v[96:111]
	v_add_f32_e32 v14, v197, v80
	v_exp_f32_e32 v80, v14
	v_add_f32_e32 v15, v197, v81
	v_exp_f32_e32 v81, v15
	s_waitcnt lgkmcnt(4)
	v_mfma_f32_32x32x16_bf16 v[96:111], v[160:163], v[144:147], v[96:111]
	ds_read_b128 v[2:5], v0 offset:13056
	ds_read_b128 v[6:9], v0 offset:13088
	ds_read_b128 v[10:13], v0 offset:13120
	ds_read_b128 v[160:163], v0 offset:13152
	v_add_f32_e32 v14, v197, v82
	v_exp_f32_e32 v82, v14
	v_add_f32_e32 v15, v197, v83
	v_exp_f32_e32 v83, v15
	s_waitcnt lgkmcnt(7)
	v_mfma_f32_32x32x16_bf16 v[96:111], v[164:167], v[140:143], v[96:111]
	v_add_f32_e32 v14, v197, v84
	v_exp_f32_e32 v84, v14
	v_add_f32_e32 v15, v197, v85
	v_exp_f32_e32 v85, v15
	s_waitcnt lgkmcnt(6)
	v_mfma_f32_32x32x16_bf16 v[96:111], v[168:171], v[136:139], v[96:111]
	v_add_f32_e32 v14, v197, v86
	v_exp_f32_e32 v86, v14
	v_add_f32_e32 v15, v197, v87
	v_exp_f32_e32 v87, v15
	s_waitcnt lgkmcnt(5)
	v_mfma_f32_32x32x16_bf16 v[96:111], v[172:175], v[132:135], v[96:111]
	v_add_f32_e32 v14, v197, v88
	v_exp_f32_e32 v88, v14
	v_add_f32_e32 v15, v197, v89
	v_exp_f32_e32 v89, v15
	s_waitcnt lgkmcnt(4)
	v_mfma_f32_32x32x16_bf16 v[96:111], v[176:179], v[128:131], v[96:111]
	v_add_f32_e32 v14, v197, v90
	v_exp_f32_e32 v90, v14
	v_add_f32_e32 v15, v197, v91
	v_exp_f32_e32 v91, v15
	s_waitcnt lgkmcnt(3)
	v_mfma_f32_32x32x16_bf16 v[96:111], v[2:5], v[124:127], v[96:111]
	v_add_f32_e32 v14, v197, v92
	v_exp_f32_e32 v92, v14
	v_add_f32_e32 v15, v197, v93
	v_exp_f32_e32 v93, v15
	s_waitcnt lgkmcnt(2)
	v_mfma_f32_32x32x16_bf16 v[96:111], v[6:9], v[120:123], v[96:111]
	v_add_f32_e32 v14, v197, v94
	v_exp_f32_e32 v94, v14
	v_add_f32_e32 v15, v197, v95
	v_exp_f32_e32 v95, v15
	s_waitcnt lgkmcnt(1)
	v_mfma_f32_32x32x16_bf16 v[96:111], v[10:13], v[116:119], v[96:111]
	v_cvt_pk_bf16_f32 v186, v80, v81
	v_cvt_pk_bf16_f32 v187, v82, v83
	v_cvt_pk_bf16_f32 v188, v84, v85
	v_cvt_pk_bf16_f32 v189, v86, v87
	s_waitcnt lgkmcnt(0)
	v_mfma_f32_32x32x16_bf16 v[96:111], v[160:163], v[112:115], v[96:111]
	v_cvt_pk_bf16_f32 v214, v88, v89
	v_cvt_pk_bf16_f32 v215, v90, v91
	v_cvt_pk_bf16_f32 v216, v92, v93
	v_cvt_pk_bf16_f32 v217, v94, v95
	v_lshlrev_b32_e32 v0, 1, v233
	v_add3_u32 v15, s35, v234, v0
	v_add_u32_e32 v176, 0x6000, v15
	v_add_u32_e32 v180, 0x7000, v15
	ds_read2_b64 v[2:5], v176 offset0:128 offset1:130
	ds_read2_b64 v[6:9], v176 offset0:132 offset1:134
	ds_read2_b64 v[10:13], v180 offset0:160 offset1:162
	ds_read2_b64 v[172:175], v180 offset0:164 offset1:166
	v_add_u32_e32 v0, s34, v248
	v_mad_i64_i32 v[192:193], s[0:1], v0, s7, v[208:209]
	global_load_dwordx4 v[164:167], v[192:193], off
	v_add_u32_e32 v0, s34, v247
	v_mad_i64_i32 v[192:193], s[0:1], v0, s7, v[210:211]
	global_load_dwordx4 v[160:163], v[192:193], off
	v_add_u32_e32 v0, s34, v246
	v_mad_i64_i32 v[192:193], s[0:1], v0, s7, v[212:213]
	global_load_dwordx4 v[168:171], v[192:193], off
	s_add_i32 s4, s34, 64
	s_waitcnt lgkmcnt(3)
;     ...
;         if (active) {
;             const bool masked = (k0 + 63 > q0); const int qpos = q0 + r;
; #pragma unroll
;             for (int kb = 0; kb < 2; ++kb) {
;                 bf16x8 vfa[2][2], vfb[2][2];
; #pragma unroll
;                 for (int d = 0; d < 2; ++d) { vfa[d][0] = ld_perm(Vs + (32 * d + r) * VLD + 32 * kb + 4 * h2); vfa[d][1] = ld_perm(Vs + (32 * d + r) * VLD + 32 * kb + 16 + 4 * h2); }
;                 f32x4 c4[2];
;                 if (DECAY) {
; #pragma unroll
;                     for (int g = 0; g < 2; ++g) c4[g] = *(const f32x4*)(cks + 32 * kb + 8 * g + 4 * h2); }
;                 __builtin_amdgcn_sched_barrier(0);
;                 if (DECAY) {
; #pragma unroll
;                     for (int g = 0; g < 2; ++g)
; #pragma unroll
;                         for (int e = 0; e < 4; ++e) sacc[kb][4 * g + e] -= c4[g][e];
; #pragma unroll
;                     for (int g = 0; g < 2; ++g) c4[g] = *(const f32x4*)(cks + 32 * kb + 8 * (g + 2) + 4 * h2);
; #pragma unroll
;                     for (int g = 0; g < 2; ++g)
; #pragma unroll
;                         for (int e = 0; e < 4; ++e) sacc[kb][4 * (g + 2) + e] -= c4[g][e];
;                 }
;                 if (masked) {
; #pragma unroll
;                     for (int i = 0; i < 16; ++i) { if (k0 + 32 * kb + crow(i, h2) > qpos) sacc[kb][i] = -INFINITY; } }
;                 float rs = 0.f;
; #pragma unroll
;                 for (int i = 0; i < 16; ++i) { const float pz = __builtin_amdgcn_exp2f(sacc[kb][i] + c0); sacc[kb][i] = pz; rs += pz; }
;                 l_run += rs;
;                 const bf16x8 pf0 = pack8(sacc[kb], 0), pf1 = pack8(sacc[kb], 1);
;                 __builtin_amdgcn_sched_barrier(0);
; #pragma unroll
;                 for (int d = 0; d < 2; ++d) { oacc[d] = MFMA32(vfa[d][0], pf0, oacc[d]); oacc[d] = MFMA32(vfa[d][1], pf1, oacc[d]); }
; #pragma unroll
;                 for (int d = 0; d < 2; ++d) { vfb[d][0] = ld_perm(Vs + (32 * (d + 2) + r) * VLD + 32 * kb + 4 * h2); vfb[d][1] = ld_perm(Vs + (32 * (d + 2) + r) * VLD + 32 * kb + 16 + 4 * h2); }
;                 if (kb == 1 && j + 1 < ntiles && amode != 5) ATT_ISSUE_V(j + 1);
;                 __builtin_amdgcn_sched_barrier(0);
; #pragma unroll
;                 for (int d = 0; d < 2; ++d) { oacc[d + 2] = MFMA32(vfb[d][0], pf0, oacc[d + 2]); oacc[d + 2] = MFMA32(vfb[d][1], pf1, oacc[d + 2]); }
;             }
	v_mfma_f32_32x32x16_bf16 v[64:79], v[2:5], v[186:189], v[64:79]
	v_add_u32_e32 v0, 0x9000, v15
	v_add_u32_e32 v15, 0x8000, v15
	v_add_f32_e32 v14, v197, v96
	v_exp_f32_e32 v96, v14
	v_add_f32_e32 v192, v197, v97
	v_exp_f32_e32 v97, v192
	s_waitcnt lgkmcnt(1)
	v_mfma_f32_32x32x16_bf16 v[48:63], v[10:13], v[186:189], v[48:63]
	v_add_f32_e32 v14, v197, v98
	v_exp_f32_e32 v98, v14
	v_add_f32_e32 v192, v197, v99
	v_exp_f32_e32 v99, v192
	v_mfma_f32_32x32x16_bf16 v[64:79], v[6:9], v[214:217], v[64:79]
	ds_read2_b64 v[2:5], v0 offset0:228 offset1:230
	ds_read2_b64 v[6:9], v0 offset0:224 offset1:226
	v_add_f32_e32 v14, v197, v100
	v_exp_f32_e32 v100, v14
	v_add_f32_e32 v192, v197, v101
	v_exp_f32_e32 v101, v192
	s_waitcnt lgkmcnt(2)
	v_mfma_f32_32x32x16_bf16 v[48:63], v[172:175], v[214:217], v[48:63]
	ds_read2_b64 v[10:13], v15 offset0:192 offset1:194
	ds_read2_b64 v[172:175], v15 offset0:196 offset1:198
	v_add_f32_e32 v14, v197, v102
	v_exp_f32_e32 v102, v14
	v_add_f32_e32 v192, v197, v103
	v_exp_f32_e32 v103, v192
	s_waitcnt lgkmcnt(1)
	v_mfma_f32_32x32x16_bf16 v[32:47], v[10:13], v[186:189], v[32:47]
	v_add_f32_e32 v14, v197, v104
	v_exp_f32_e32 v104, v14
	v_add_f32_e32 v192, v197, v105
	v_exp_f32_e32 v105, v192
	v_mfma_f32_32x32x16_bf16 v[16:31], v[6:9], v[186:189], v[16:31]
	v_add_f32_e32 v14, v197, v106
	v_exp_f32_e32 v106, v14
	v_add_f32_e32 v192, v197, v107
	v_exp_f32_e32 v107, v192
	s_waitcnt lgkmcnt(0)
	v_mfma_f32_32x32x16_bf16 v[32:47], v[172:175], v[214:217], v[32:47]
	ds_read2_b64 v[10:13], v176 offset0:136 offset1:138
	ds_read2_b64 v[172:175], v176 offset0:140 offset1:142
	ds_read2_b64 v[176:179], v180 offset0:168 offset1:170
	ds_read2_b64 v[180:183], v180 offset0:172 offset1:174
	v_add_f32_e32 v14, v197, v108
	v_exp_f32_e32 v108, v14
	v_add_f32_e32 v192, v197, v109
	v_exp_f32_e32 v109, v192
	v_mfma_f32_32x32x16_bf16 v[16:31], v[2:5], v[214:217], v[16:31]
	v_add_f32_e32 v14, v197, v110
	v_exp_f32_e32 v110, v14
	v_add_f32_e32 v192, v197, v111
	v_exp_f32_e32 v111, v192
	v_cvt_pk_bf16_f32 v2, v96, v97
	v_cvt_pk_bf16_f32 v3, v98, v99
	v_cvt_pk_bf16_f32 v4, v100, v101
	v_cvt_pk_bf16_f32 v5, v102, v103
	v_cvt_pk_bf16_f32 v6, v104, v105
	v_cvt_pk_bf16_f32 v7, v106, v107
	v_cvt_pk_bf16_f32 v8, v108, v109
	v_cvt_pk_bf16_f32 v9, v110, v111
	v_lshl_add_u64 v[186:187], s[4:5], 1, v[202:203]
	v_lshl_add_u64 v[188:189], v[186:187], 0, v[204:205]
	v_lshl_add_u64 v[186:187], v[186:187], 0, v[206:207]
	s_waitcnt lgkmcnt(3)
	v_mfma_f32_32x32x16_bf16 v[64:79], v[10:13], v[2:5], v[64:79]
	v_add_f32_e32 v14, 0, v80
	v_add_f32_e32 v192, 0, v96
	v_add_f32_e32 v14, v81, v14
	v_add_f32_e32 v192, v97, v192
	s_waitcnt lgkmcnt(1)
	v_mfma_f32_32x32x16_bf16 v[48:63], v[176:179], v[2:5], v[48:63]
	v_add_f32_e32 v14, v82, v14
	v_add_f32_e32 v192, v98, v192
	v_add_f32_e32 v14, v83, v14
	v_add_f32_e32 v192, v99, v192
	v_mfma_f32_32x32x16_bf16 v[64:79], v[172:175], v[6:9], v[64:79]
	v_add_f32_e32 v14, v84, v14
	v_add_f32_e32 v192, v100, v192
	v_add_f32_e32 v14, v85, v14
	v_add_f32_e32 v192, v101, v192
	s_waitcnt lgkmcnt(0)
	v_mfma_f32_32x32x16_bf16 v[48:63], v[180:183], v[6:9], v[48:63]
	global_load_dwordx4 v[172:175], v[186:187], off
	global_load_dwordx4 v[176:179], v[188:189], off
	ds_read2_b64 v[10:13], v15 offset0:200 offset1:202
	ds_read2_b64 v[180:183], v15 offset0:204 offset1:206
	ds_read2_b64 v[186:189], v0 offset0:232 offset1:234
	ds_read2_b64 v[214:217], v0 offset0:236 offset1:238
	v_add_f32_e32 v14, v86, v14
	v_add_f32_e32 v192, v102, v192
	v_add_f32_e32 v14, v87, v14
	v_add_f32_e32 v192, v103, v192
	s_waitcnt lgkmcnt(3)
	v_mfma_f32_32x32x16_bf16 v[32:47], v[10:13], v[2:5], v[32:47]
	v_add_f32_e32 v14, v88, v14
	v_add_f32_e32 v192, v104, v192
	v_add_f32_e32 v14, v89, v14
	v_add_f32_e32 v192, v105, v192
	s_waitcnt lgkmcnt(1)
	v_mfma_f32_32x32x16_bf16 v[16:31], v[186:189], v[2:5], v[16:31]
	v_add_f32_e32 v14, v90, v14
	v_add_f32_e32 v192, v106, v192
	v_add_f32_e32 v14, v91, v14
	v_add_f32_e32 v192, v107, v192
	v_mfma_f32_32x32x16_bf16 v[32:47], v[180:183], v[6:9], v[32:47]
	v_add_f32_e32 v14, v92, v14
	v_add_f32_e32 v192, v108, v192
	v_add_f32_e32 v14, v93, v14
	v_add_f32_e32 v192, v109, v192
	s_waitcnt lgkmcnt(0)
	v_mfma_f32_32x32x16_bf16 v[16:31], v[214:217], v[6:9], v[16:31]
	v_add_f32_e32 v14, v94, v14
	v_add_f32_e32 v192, v110, v192
	v_add_f32_e32 v14, v95, v14
	v_add_f32_e32 v192, v111, v192
	v_add_f32_e32 v193, v199, v14
	v_add_f32_e32 v199, v193, v192
	s_branch .LBB0_301
.Ltramp_627:
	s_branch .LBB0_627
.LBB0_303:
	s_mov_b64 s[0:1], 0
